# v36: v31 + static priority stagger in the attention mixers, waves 0-3 raised (s_setprio 1), reset at GEMM unit headers
# speedup vs baseline: 1.0080x; 1.0003x over previous
.LBB0_449:
	s_bitcmp1_b32 s60, 8
	s_cbranch_scc1 .Lmixprio_skip
	s_setprio 1
